# speedup vs baseline: 1.0043x; 1.0043x over previous
; DI unsigned pk2(float lo, float hi) { const f32x2_t v = {lo, hi}; const bf16x2_t b = __builtin_convertvector(v, bf16x2_t); return __builtin_bit_cast(unsigned, b); }
; DI float rowscale(const float* ss, int row) {
;     const f32x4* p = (const f32x4*)(ss + (size_t)row * 16);
;     const f32x4 a = p[0], b = p[1], c = p[2], d = p[3];
;     const float s = (((a.x + a.y) + (a.z + a.w)) + ((b.x + b.y) + (b.z + b.w))) + (((c.x + c.y) + (c.z + c.w)) + ((d.x + d.y) + (d.z + d.w)));
;     return rsqrtf(s * (1.0f / 1024.0f) + EPS);
; }
; DI void rowscales8(const float* ss, int rowbase, int fr, int fq, float (&r)[2][4]) {
;     const int lane = fq * 16 + fr;
;     const float rA = rowscale(ss, rowbase + lane), rB = rowscale(ss, rowbase + 128 + lane);
; #pragma unroll
;     for (int m = 0; m < 4; ++m) { r[0][m] = __shfl(rA, m * 16 + fr); r[1][m] = __shfl(rB, m * 16 + fr); }
; }
;     DI void operator()(const pg8::f32x4 (&acc)[2][2][4][2], const pg8::Unit& u, int wr, int wc, int fr, int fq) const {
;         const int row0 = u.pm * 256 + wr * 64 + fr, col0 = u.pn * 128 + wc * 32 + 8 * fq;
;         float rs[2][4]; rowscales8(ss, u.pm * 256 + wr * 64, fr, fq, rs);
; #pragma unroll
;         for (int ai = 0; ai < 2; ++ai)
; #pragma unroll
;             for (int m = 0; m < 4; ++m) {
;                 const int row = row0 + ai * 128 + m * 16; const float r = rs[ai][m];
;                 float hv[8];
; #pragma unroll
;                 for (int n = 0; n < 2; ++n) { const pg8::f32x4 g = acc[ai][0][m][n] * r, uu = acc[ai][1][m][n] * r;
; #pragma unroll
;                     for (int e = 0; e < 4; ++e) hv[4 * n + e] = g[e] * __frcp_rn(1.0f + __expf(-g[e])) * uu[e]; }
;                 u32x4 w; w.x = pk2(hv[0], hv[1]); w.y = pk2(hv[2], hv[3]); w.z = pk2(hv[4], hv[5]); w.w = pk2(hv[6], hv[7]);
;                 *(u32x4*)(H + (size_t)row * DFF + col0) = w;
.Lmy_kdone_2:
.LBB0_520:
	s_lshl_b32 s9, s16, 8
	s_add_i32 s9, s9, s48
	v_or_b32_e32 v154, s9, v143
	v_ashrrev_i32_e32 v155, 31, v154
	v_lshlrev_b64 v[154:155], 6, v[154:155]
	v_lshl_add_u64 v[158:159], s[4:5], 0, v[154:155]
	global_load_dwordx4 v[154:157], v[158:159], off offset:16
	global_load_dwordx4 v[162:165], v[158:159], off offset:48
	global_load_dwordx4 v[166:169], v[158:159], off
	global_load_dwordx4 v[170:173], v[158:159], off offset:32
	v_add_u32_e32 v232, s9, v145
	v_ashrrev_i32_e32 v233, 31, v232
	v_lshlrev_b64 v[232:233], 6, v[232:233]
	v_lshl_add_u64 v[230:231], s[4:5], 0, v[232:233]
	global_load_dwordx4 v[214:217], v[230:231], off offset:16
	global_load_dwordx4 v[218:221], v[230:231], off offset:48
	global_load_dwordx4 v[222:225], v[230:231], off
	global_load_dwordx4 v[226:229], v[230:231], off offset:32
	s_mov_b32 s16, 0x3a800000
	v_lshl_or_b32 v152, s17, 7, v147
	v_or_b32_e32 v151, s9, v139
	s_mul_i32 s11, s88, 56
	s_waitcnt vmcnt(4)
	v_mov_b32_e32 v158, v166
	v_mov_b32_e32 v159, v170
	v_mov_b32_e32 v170, v167
	v_mov_b32_e32 v166, v168
	v_mov_b32_e32 v167, v172
	v_mov_b32_e32 v172, v169
	v_pk_add_f32 v[158:159], v[158:159], v[170:171]
	v_pk_add_f32 v[166:167], v[166:167], v[172:173]
	v_pk_add_f32 v[158:159], v[158:159], v[166:167]
	v_mov_b32_e32 v166, v154
	v_mov_b32_e32 v167, v162
	v_mov_b32_e32 v162, v155
	v_pk_add_f32 v[154:155], v[166:167], v[162:163]
	v_mov_b32_e32 v162, v156
	v_mov_b32_e32 v163, v164
	v_mov_b32_e32 v164, v157
	v_pk_add_f32 v[156:157], v[162:163], v[164:165]
	v_pk_add_f32 v[154:155], v[154:155], v[156:157]
	v_pk_add_f32 v[158:159], v[158:159], v[154:155]
	s_waitcnt vmcnt(0)
	v_mov_b64_e32 v[154:155], v[214:215]
	v_mov_b64_e32 v[156:157], v[216:217]
	v_mov_b64_e32 v[162:163], v[218:219]
	v_mov_b64_e32 v[164:165], v[220:221]
	v_mov_b64_e32 v[166:167], v[222:223]
	v_mov_b64_e32 v[168:169], v[224:225]
	v_mov_b64_e32 v[170:171], v[226:227]
	v_mov_b64_e32 v[172:173], v[228:229]
	s_movk_i32 s9, 0x1600
	v_mov_b32_e32 v174, v166
	v_mov_b32_e32 v175, v170
	v_mov_b32_e32 v170, v167
	v_pk_add_f32 v[166:167], v[174:175], v[170:171]
	v_mov_b32_e32 v170, v168
	v_mov_b32_e32 v171, v172
	v_mov_b32_e32 v172, v169
	v_pk_add_f32 v[168:169], v[170:171], v[172:173]
	v_pk_add_f32 v[166:167], v[166:167], v[168:169]
	v_mov_b32_e32 v168, v154
	v_mov_b32_e32 v169, v162
	v_mov_b32_e32 v162, v155
	v_pk_add_f32 v[154:155], v[168:169], v[162:163]
	v_mov_b32_e32 v162, v156
	v_mov_b32_e32 v163, v164
	v_mov_b32_e32 v164, v157
	v_pk_add_f32 v[156:157], v[162:163], v[164:165]
	v_pk_add_f32 v[154:155], v[154:155], v[156:157]
	v_mov_b32_e32 v157, v158
	v_pk_add_f32 v[154:155], v[166:167], v[154:155]
	v_mov_b32_e32 v156, v154
	v_mov_b32_e32 v158, v155
	v_pk_add_f32 v[154:155], v[156:157], v[158:159]
	v_pk_fma_f32 v[154:155], v[154:155], s[16:17], v[176:177] op_sel_hi:[1,0,0]
	v_mul_f32_e32 v138, 0x4b800000, v155
	v_cmp_gt_f32_e64 s[42:43], s39, v155
	v_cmp_gt_f32_e32 vcc, s39, v154
	s_nop 0
	v_cndmask_b32_e64 v138, v155, v138, s[42:43]
	v_rsq_f32_e32 v138, v138
	s_nop 0
	v_mul_f32_e32 v140, 0x45800000, v138
	v_cndmask_b32_e64 v138, v138, v140, s[42:43]
	v_mul_f32_e32 v140, 0x4b800000, v154
	v_cndmask_b32_e32 v140, v154, v140, vcc
	v_rsq_f32_e32 v140, v140
	s_nop 0
	v_mul_f32_e32 v142, 0x45800000, v140
	v_cndmask_b32_e32 v153, v140, v142, vcc
	v_and_or_b32 v140, v177, 64, v139
	v_lshlrev_b32_e32 v155, 2, v140
	s_cmp_lg_u64 s[6:7], 0
	s_cbranch_scc0 .Lmy_ab2
	s_barrier
.Lmy_ab2:
	ds_bpermute_b32 v154, v155, v138
	ds_bpermute_b32 v144, v155, v153
	ds_bpermute_b32 v150, v155, v138 offset:64
	ds_bpermute_b32 v142, v155, v153 offset:64
	ds_bpermute_b32 v148, v155, v138 offset:128
	s_waitcnt lgkmcnt(4)
	v_pk_mul_f32 v[124:125], v[124:125], v[154:155] op_sel_hi:[1,0]
	ds_bpermute_b32 v140, v155, v153 offset:128
	ds_bpermute_b32 v146, v155, v138 offset:192
	ds_bpermute_b32 v138, v155, v153 offset:192
	v_mul_f32_e32 v155, 0xbfb8aa3b, v124
	v_exp_f32_e32 v156, v155
	v_mul_f32_e32 v155, 0xbfb8aa3b, v125
	v_exp_f32_e32 v157, v155
	v_ashrrev_i32_e32 v153, 31, v152
	s_waitcnt lgkmcnt(5)
	v_pk_mul_f32 v[108:109], v[108:109], v[150:151] op_sel_hi:[1,0]
	v_pk_mul_f32 v[104:105], v[104:105], v[150:151] op_sel_hi:[1,0]
	v_pk_add_f32 v[156:157], v[156:157], 1.0 op_sel_hi:[1,0]
	v_pk_mul_f32 v[106:107], v[106:107], v[150:151] op_sel_hi:[1,0]
	v_pk_mul_f32 v[100:101], v[100:101], v[150:151] op_sel_hi:[1,0]
	v_pk_mul_f32 v[96:97], v[96:97], v[150:151] op_sel_hi:[1,0]
	v_pk_mul_f32 v[98:99], v[98:99], v[150:151] op_sel_hi:[1,0]
	v_rcp_f32_e32 v157, v157
	s_waitcnt lgkmcnt(3)
	v_pk_mul_f32 v[92:93], v[92:93], v[148:149] op_sel_hi:[1,0]
	v_pk_mul_f32 v[88:89], v[88:89], v[148:149] op_sel_hi:[1,0]
	v_pk_mul_f32 v[90:91], v[90:91], v[148:149] op_sel_hi:[1,0]
	v_rcp_f32_e32 v156, v156
	s_nop 0
	v_pk_mul_f32 v[124:125], v[124:125], v[156:157]
	v_pk_mul_f32 v[120:121], v[120:121], v[154:155] op_sel_hi:[1,0]
	v_pk_mul_f32 v[84:85], v[84:85], v[148:149] op_sel_hi:[1,0]
	v_pk_mul_f32 v[120:121], v[120:121], v[124:125]
	v_pk_mul_f32 v[124:125], v[126:127], v[154:155] op_sel_hi:[1,0]
	v_pk_mul_f32 v[80:81], v[80:81], v[148:149] op_sel_hi:[1,0]
	v_mul_f32_e32 v126, 0xbfb8aa3b, v124
	v_mul_f32_e32 v127, 0xbfb8aa3b, v125
	v_exp_f32_e32 v126, v126
	v_exp_f32_e32 v127, v127
	v_pk_mul_f32 v[82:83], v[82:83], v[148:149] op_sel_hi:[1,0]
	s_waitcnt lgkmcnt(1)
; DI unsigned pk2(float lo, float hi) { const f32x2_t v = {lo, hi}; const bf16x2_t b = __builtin_convertvector(v, bf16x2_t); return __builtin_bit_cast(unsigned, b); }
;     DI void operator()(const pg8::f32x4 (&acc)[2][2][4][2], const pg8::Unit& u, int wr, int wc, int fr, int fq) const {
;     ...
; #pragma unroll
;         for (int ai = 0; ai < 2; ++ai)
; #pragma unroll
;             for (int m = 0; m < 4; ++m) {
;                 const int row = row0 + ai * 128 + m * 16; const float r = rs[ai][m];
;                 float hv[8];
; #pragma unroll
;                 for (int n = 0; n < 2; ++n) { const pg8::f32x4 g = acc[ai][0][m][n] * r, uu = acc[ai][1][m][n] * r;
; #pragma unroll
;                     for (int e = 0; e < 4; ++e) hv[4 * n + e] = g[e] * __frcp_rn(1.0f + __expf(-g[e])) * uu[e]; }
;                 u32x4 w; w.x = pk2(hv[0], hv[1]); w.y = pk2(hv[2], hv[3]); w.z = pk2(hv[4], hv[5]); w.w = pk2(hv[6], hv[7]);
;                 *(u32x4*)(H + (size_t)row * DFF + col0) = w;
	v_pk_mul_f32 v[76:77], v[76:77], v[146:147] op_sel_hi:[1,0]
	v_pk_mul_f32 v[72:73], v[72:73], v[146:147] op_sel_hi:[1,0]
	v_pk_add_f32 v[126:127], v[126:127], 1.0 op_sel_hi:[1,0]
	v_pk_mul_f32 v[74:75], v[74:75], v[146:147] op_sel_hi:[1,0]
	v_pk_mul_f32 v[68:69], v[68:69], v[146:147] op_sel_hi:[1,0]
	v_pk_mul_f32 v[64:65], v[64:65], v[146:147] op_sel_hi:[1,0]
	v_pk_mul_f32 v[66:67], v[66:67], v[146:147] op_sel_hi:[1,0]
	v_rcp_f32_e32 v127, v127
	v_pk_mul_f32 v[60:61], v[60:61], v[144:145] op_sel_hi:[1,0]
	v_pk_mul_f32 v[56:57], v[56:57], v[144:145] op_sel_hi:[1,0]
	v_pk_mul_f32 v[58:59], v[58:59], v[144:145] op_sel_hi:[1,0]
	v_rcp_f32_e32 v126, v126
	s_nop 0
	v_pk_mul_f32 v[124:125], v[124:125], v[126:127]
	v_pk_mul_f32 v[122:123], v[122:123], v[154:155] op_sel_hi:[1,0]
	v_pk_mul_f32 v[116:117], v[116:117], v[154:155] op_sel_hi:[1,0]
	v_pk_mul_f32 v[122:123], v[122:123], v[124:125]
	v_mul_f32_e32 v124, 0xbfb8aa3b, v116
	v_mul_f32_e32 v125, 0xbfb8aa3b, v117
	v_exp_f32_e32 v124, v124
	v_exp_f32_e32 v125, v125
	v_pk_mul_f32 v[52:53], v[52:53], v[144:145] op_sel_hi:[1,0]
	v_pk_mul_f32 v[48:49], v[48:49], v[144:145] op_sel_hi:[1,0]
	v_pk_mul_f32 v[50:51], v[50:51], v[144:145] op_sel_hi:[1,0]
	v_pk_add_f32 v[124:125], v[124:125], 1.0 op_sel_hi:[1,0]
	v_pk_mul_f32 v[44:45], v[44:45], v[142:143] op_sel_hi:[1,0]
	v_pk_mul_f32 v[40:41], v[40:41], v[142:143] op_sel_hi:[1,0]
	v_pk_mul_f32 v[42:43], v[42:43], v[142:143] op_sel_hi:[1,0]
	v_pk_mul_f32 v[36:37], v[36:37], v[142:143] op_sel_hi:[1,0]
	v_rcp_f32_e32 v125, v125
	v_pk_mul_f32 v[32:33], v[32:33], v[142:143] op_sel_hi:[1,0]
	v_pk_mul_f32 v[34:35], v[34:35], v[142:143] op_sel_hi:[1,0]
	v_pk_mul_f32 v[28:29], v[28:29], v[140:141] op_sel_hi:[1,0]
	v_rcp_f32_e32 v124, v124
	s_nop 0
	v_pk_mul_f32 v[116:117], v[116:117], v[124:125]
	v_pk_mul_f32 v[112:113], v[112:113], v[154:155] op_sel_hi:[1,0]
	v_pk_mul_f32 v[24:25], v[24:25], v[140:141] op_sel_hi:[1,0]
	v_pk_mul_f32 v[112:113], v[112:113], v[116:117]
	v_pk_mul_f32 v[116:117], v[118:119], v[154:155] op_sel_hi:[1,0]
	v_pk_mul_f32 v[26:27], v[26:27], v[140:141] op_sel_hi:[1,0]
	v_mul_f32_e32 v118, 0xbfb8aa3b, v116
	v_mul_f32_e32 v119, 0xbfb8aa3b, v117
	v_exp_f32_e32 v118, v118
	v_exp_f32_e32 v119, v119
	v_pk_mul_f32 v[20:21], v[20:21], v[140:141] op_sel_hi:[1,0]
	v_pk_mul_f32 v[16:17], v[16:17], v[140:141] op_sel_hi:[1,0]
	v_pk_mul_f32 v[18:19], v[18:19], v[140:141] op_sel_hi:[1,0]
	v_pk_add_f32 v[118:119], v[118:119], 1.0 op_sel_hi:[1,0]
	s_waitcnt lgkmcnt(0)
	v_pk_mul_f32 v[12:13], v[12:13], v[138:139] op_sel_hi:[1,0]
	v_pk_mul_f32 v[8:9], v[8:9], v[138:139] op_sel_hi:[1,0]
	v_pk_mul_f32 v[10:11], v[10:11], v[138:139] op_sel_hi:[1,0]
	v_pk_mul_f32 v[4:5], v[4:5], v[138:139] op_sel_hi:[1,0]
	v_rcp_f32_e32 v119, v119
	v_pk_mul_f32 v[0:1], v[0:1], v[138:139] op_sel_hi:[1,0]
	v_pk_mul_f32 v[2:3], v[2:3], v[138:139] op_sel_hi:[1,0]
	v_rcp_f32_e32 v118, v118
	s_nop 0
	v_pk_mul_f32 v[116:117], v[116:117], v[118:119]
	v_pk_mul_f32 v[114:115], v[114:115], v[154:155] op_sel_hi:[1,0]
	v_cvt_pk_bf16_f32 v118, v112, v113
	v_pk_mul_f32 v[114:115], v[114:115], v[116:117]
	v_mov_b64_e32 v[112:113], s[82:83]
	v_cvt_pk_bf16_f32 v116, v120, v121
	v_cvt_pk_bf16_f32 v119, v114, v115
	v_mad_i64_i32 v[120:121], s[16:17], v151, s9, v[112:113]
	v_lshlrev_b64 v[114:115], 1, v[152:153]
	v_cvt_pk_bf16_f32 v117, v122, v123
	v_lshl_add_u64 v[120:121], v[120:121], 0, v[114:115]
	global_store_dwordx4 v[120:121], v[116:119], off
	s_nop 1
	v_mul_f32_e32 v116, 0xbfb8aa3b, v108
	v_mul_f32_e32 v117, 0xbfb8aa3b, v109
	v_exp_f32_e32 v116, v116
	v_exp_f32_e32 v117, v117
	s_nop 0
	v_pk_add_f32 v[116:117], v[116:117], 1.0 op_sel_hi:[1,0]
	v_rcp_f32_e32 v117, v117
	v_rcp_f32_e32 v116, v116
	s_nop 0
	v_pk_mul_f32 v[108:109], v[108:109], v[116:117]
	v_pk_mul_f32 v[104:105], v[104:105], v[108:109]
	v_pk_mul_f32 v[108:109], v[110:111], v[150:151] op_sel_hi:[1,0]
	v_mul_f32_e32 v110, 0xbfb8aa3b, v108
	v_mul_f32_e32 v111, 0xbfb8aa3b, v109
	v_exp_f32_e32 v110, v110
	v_exp_f32_e32 v111, v111
	s_nop 0
	v_pk_add_f32 v[110:111], v[110:111], 1.0 op_sel_hi:[1,0]
	v_rcp_f32_e32 v111, v111
	v_rcp_f32_e32 v110, v110
	s_nop 0
	v_pk_mul_f32 v[108:109], v[108:109], v[110:111]
	v_pk_mul_f32 v[106:107], v[106:107], v[108:109]
	v_mul_f32_e32 v108, 0xbfb8aa3b, v100
	v_mul_f32_e32 v109, 0xbfb8aa3b, v101
	v_exp_f32_e32 v108, v108
	v_exp_f32_e32 v109, v109
	s_nop 0
	v_pk_add_f32 v[108:109], v[108:109], 1.0 op_sel_hi:[1,0]
	v_rcp_f32_e32 v109, v109
	v_rcp_f32_e32 v108, v108
	s_nop 0
	v_pk_mul_f32 v[100:101], v[100:101], v[108:109]
	v_pk_mul_f32 v[100:101], v[96:97], v[100:101]
	v_pk_mul_f32 v[96:97], v[102:103], v[150:151] op_sel_hi:[1,0]
	v_mul_f32_e32 v102, 0xbfb8aa3b, v96
	v_mul_f32_e32 v103, 0xbfb8aa3b, v97
	v_exp_f32_e32 v102, v102
	v_exp_f32_e32 v103, v103
	s_nop 0
	v_pk_add_f32 v[102:103], v[102:103], 1.0 op_sel_hi:[1,0]
	v_rcp_f32_e32 v103, v103
	v_rcp_f32_e32 v102, v102
	s_nop 0
	v_pk_mul_f32 v[96:97], v[96:97], v[102:103]
	v_or_b32_e32 v108, 16, v151
	v_pk_mul_f32 v[102:103], v[98:99], v[96:97]
	v_cvt_pk_bf16_f32 v98, v100, v101
	v_mad_i64_i32 v[100:101], s[16:17], v108, s9, v[112:113]
	v_cvt_pk_bf16_f32 v96, v104, v105
	v_cvt_pk_bf16_f32 v97, v106, v107
	v_cvt_pk_bf16_f32 v99, v102, v103
	v_lshl_add_u64 v[100:101], v[100:101], 0, v[114:115]
	global_store_dwordx4 v[100:101], v[96:99], off
	s_nop 1
	v_mul_f32_e32 v96, 0xbfb8aa3b, v92
	v_mul_f32_e32 v97, 0xbfb8aa3b, v93
	v_exp_f32_e32 v96, v96
	v_exp_f32_e32 v97, v97
	s_nop 0
	v_pk_add_f32 v[96:97], v[96:97], 1.0 op_sel_hi:[1,0]
	v_rcp_f32_e32 v97, v97
	v_rcp_f32_e32 v96, v96
	s_nop 0
	v_pk_mul_f32 v[92:93], v[92:93], v[96:97]
	v_pk_mul_f32 v[88:89], v[88:89], v[92:93]
; DI unsigned pk2(float lo, float hi) { const f32x2_t v = {lo, hi}; const bf16x2_t b = __builtin_convertvector(v, bf16x2_t); return __builtin_bit_cast(unsigned, b); }
;     DI void operator()(const pg8::f32x4 (&acc)[2][2][4][2], const pg8::Unit& u, int wr, int wc, int fr, int fq) const {
;     ...
;             for (int m = 0; m < 4; ++m) {
;                 const int row = row0 + ai * 128 + m * 16; const float r = rs[ai][m];
;                 float hv[8];
; #pragma unroll
;                 for (int n = 0; n < 2; ++n) { const pg8::f32x4 g = acc[ai][0][m][n] * r, uu = acc[ai][1][m][n] * r;
; #pragma unroll
;                     for (int e = 0; e < 4; ++e) hv[4 * n + e] = g[e] * __frcp_rn(1.0f + __expf(-g[e])) * uu[e]; }
;                 u32x4 w; w.x = pk2(hv[0], hv[1]); w.y = pk2(hv[2], hv[3]); w.z = pk2(hv[4], hv[5]); w.w = pk2(hv[6], hv[7]);
;                 *(u32x4*)(H + (size_t)row * DFF + col0) = w;
	v_pk_mul_f32 v[92:93], v[94:95], v[148:149] op_sel_hi:[1,0]
	v_mul_f32_e32 v94, 0xbfb8aa3b, v92
	v_mul_f32_e32 v95, 0xbfb8aa3b, v93
	v_exp_f32_e32 v94, v94
	v_exp_f32_e32 v95, v95
	s_nop 0
	v_pk_add_f32 v[94:95], v[94:95], 1.0 op_sel_hi:[1,0]
	v_rcp_f32_e32 v95, v95
	v_rcp_f32_e32 v94, v94
	s_nop 0
	v_pk_mul_f32 v[92:93], v[92:93], v[94:95]
	v_pk_mul_f32 v[90:91], v[90:91], v[92:93]
	v_mul_f32_e32 v92, 0xbfb8aa3b, v84
	v_mul_f32_e32 v93, 0xbfb8aa3b, v85
	v_exp_f32_e32 v92, v92
	v_exp_f32_e32 v93, v93
	s_nop 0
	v_pk_add_f32 v[92:93], v[92:93], 1.0 op_sel_hi:[1,0]
	v_rcp_f32_e32 v93, v93
	v_rcp_f32_e32 v92, v92
	s_nop 0
	v_pk_mul_f32 v[84:85], v[84:85], v[92:93]
	v_pk_mul_f32 v[84:85], v[80:81], v[84:85]
	v_pk_mul_f32 v[80:81], v[86:87], v[148:149] op_sel_hi:[1,0]
	v_mul_f32_e32 v86, 0xbfb8aa3b, v80
	v_mul_f32_e32 v87, 0xbfb8aa3b, v81
	v_exp_f32_e32 v86, v86
	v_exp_f32_e32 v87, v87
	s_nop 0
	v_pk_add_f32 v[86:87], v[86:87], 1.0 op_sel_hi:[1,0]
	v_rcp_f32_e32 v87, v87
	v_rcp_f32_e32 v86, v86
	s_nop 0
	v_pk_mul_f32 v[80:81], v[80:81], v[86:87]
	v_or_b32_e32 v92, 32, v151
	v_pk_mul_f32 v[86:87], v[82:83], v[80:81]
	v_cvt_pk_bf16_f32 v82, v84, v85
	v_mad_i64_i32 v[84:85], s[16:17], v92, s9, v[112:113]
	v_cvt_pk_bf16_f32 v80, v88, v89
	v_cvt_pk_bf16_f32 v81, v90, v91
	v_cvt_pk_bf16_f32 v83, v86, v87
	v_lshl_add_u64 v[84:85], v[84:85], 0, v[114:115]
	global_store_dwordx4 v[84:85], v[80:83], off
	s_nop 1
	v_mul_f32_e32 v80, 0xbfb8aa3b, v76
	v_mul_f32_e32 v81, 0xbfb8aa3b, v77
	v_exp_f32_e32 v80, v80
	v_exp_f32_e32 v81, v81
	s_nop 0
	v_pk_add_f32 v[80:81], v[80:81], 1.0 op_sel_hi:[1,0]
	v_rcp_f32_e32 v81, v81
	v_rcp_f32_e32 v80, v80
	s_nop 0
	v_pk_mul_f32 v[76:77], v[76:77], v[80:81]
	v_pk_mul_f32 v[72:73], v[72:73], v[76:77]
	v_pk_mul_f32 v[76:77], v[78:79], v[146:147] op_sel_hi:[1,0]
	v_mul_f32_e32 v78, 0xbfb8aa3b, v76
	v_mul_f32_e32 v79, 0xbfb8aa3b, v77
	v_exp_f32_e32 v78, v78
	v_exp_f32_e32 v79, v79
	s_nop 0
	v_pk_add_f32 v[78:79], v[78:79], 1.0 op_sel_hi:[1,0]
	v_rcp_f32_e32 v79, v79
	v_rcp_f32_e32 v78, v78
	s_nop 0
	v_pk_mul_f32 v[76:77], v[76:77], v[78:79]
	v_pk_mul_f32 v[74:75], v[74:75], v[76:77]
	v_mul_f32_e32 v76, 0xbfb8aa3b, v68
	v_mul_f32_e32 v77, 0xbfb8aa3b, v69
	v_exp_f32_e32 v76, v76
	v_exp_f32_e32 v77, v77
	s_nop 0
	v_pk_add_f32 v[76:77], v[76:77], 1.0 op_sel_hi:[1,0]
	v_rcp_f32_e32 v77, v77
	v_rcp_f32_e32 v76, v76
	s_nop 0
	v_pk_mul_f32 v[68:69], v[68:69], v[76:77]
	v_pk_mul_f32 v[68:69], v[64:65], v[68:69]
	v_pk_mul_f32 v[64:65], v[70:71], v[146:147] op_sel_hi:[1,0]
	v_mul_f32_e32 v70, 0xbfb8aa3b, v64
	v_mul_f32_e32 v71, 0xbfb8aa3b, v65
	v_exp_f32_e32 v70, v70
	v_exp_f32_e32 v71, v71
	s_nop 0
	v_pk_add_f32 v[70:71], v[70:71], 1.0 op_sel_hi:[1,0]
	v_rcp_f32_e32 v71, v71
	v_rcp_f32_e32 v70, v70
	s_nop 0
	v_pk_mul_f32 v[64:65], v[64:65], v[70:71]
	v_or_b32_e32 v76, 48, v151
	v_pk_mul_f32 v[70:71], v[66:67], v[64:65]
	v_cvt_pk_bf16_f32 v66, v68, v69
	v_mad_i64_i32 v[68:69], s[16:17], v76, s9, v[112:113]
	v_cvt_pk_bf16_f32 v64, v72, v73
	v_cvt_pk_bf16_f32 v65, v74, v75
	v_cvt_pk_bf16_f32 v67, v70, v71
	v_lshl_add_u64 v[68:69], v[68:69], 0, v[114:115]
	global_store_dwordx4 v[68:69], v[64:67], off
	s_nop 1
	v_mul_f32_e32 v64, 0xbfb8aa3b, v60
	v_mul_f32_e32 v65, 0xbfb8aa3b, v61
	v_exp_f32_e32 v64, v64
	v_exp_f32_e32 v65, v65
	v_add_u32_e32 v66, 0x80, v151
	v_pk_add_f32 v[64:65], v[64:65], 1.0 op_sel_hi:[1,0]
	v_rcp_f32_e32 v65, v65
	v_rcp_f32_e32 v64, v64
	s_nop 0
	v_pk_mul_f32 v[60:61], v[60:61], v[64:65]
	v_pk_mul_f32 v[56:57], v[56:57], v[60:61]
	v_pk_mul_f32 v[60:61], v[62:63], v[144:145] op_sel_hi:[1,0]
	v_mul_f32_e32 v62, 0xbfb8aa3b, v60
	v_mul_f32_e32 v63, 0xbfb8aa3b, v61
	v_exp_f32_e32 v62, v62
	v_exp_f32_e32 v63, v63
	s_nop 0
	v_pk_add_f32 v[62:63], v[62:63], 1.0 op_sel_hi:[1,0]
	v_rcp_f32_e32 v63, v63
	v_rcp_f32_e32 v62, v62
	s_nop 0
	v_pk_mul_f32 v[60:61], v[60:61], v[62:63]
	v_pk_mul_f32 v[58:59], v[58:59], v[60:61]
	v_mul_f32_e32 v60, 0xbfb8aa3b, v52
	v_mul_f32_e32 v61, 0xbfb8aa3b, v53
	v_exp_f32_e32 v60, v60
	v_exp_f32_e32 v61, v61
	s_nop 0
	v_pk_add_f32 v[60:61], v[60:61], 1.0 op_sel_hi:[1,0]
	v_rcp_f32_e32 v61, v61
	v_rcp_f32_e32 v60, v60
	s_nop 0
	v_pk_mul_f32 v[52:53], v[52:53], v[60:61]
	v_pk_mul_f32 v[52:53], v[48:49], v[52:53]
	v_pk_mul_f32 v[48:49], v[54:55], v[144:145] op_sel_hi:[1,0]
	v_mul_f32_e32 v54, 0xbfb8aa3b, v48
	v_mul_f32_e32 v55, 0xbfb8aa3b, v49
	v_exp_f32_e32 v54, v54
	v_exp_f32_e32 v55, v55
	s_nop 0
	v_pk_add_f32 v[54:55], v[54:55], 1.0 op_sel_hi:[1,0]
	v_rcp_f32_e32 v55, v55
	v_rcp_f32_e32 v54, v54
	s_nop 0
	v_pk_mul_f32 v[48:49], v[48:49], v[54:55]
	v_pk_mul_f32 v[54:55], v[50:51], v[48:49]
	v_cvt_pk_bf16_f32 v50, v52, v53
	v_mad_i64_i32 v[52:53], s[16:17], v66, s9, v[112:113]
	v_cvt_pk_bf16_f32 v48, v56, v57
	v_cvt_pk_bf16_f32 v49, v58, v59
	v_cvt_pk_bf16_f32 v51, v54, v55
	v_lshl_add_u64 v[52:53], v[52:53], 0, v[114:115]
	global_store_dwordx4 v[52:53], v[48:51], off
	s_nop 1
	v_mul_f32_e32 v48, 0xbfb8aa3b, v44
	v_mul_f32_e32 v49, 0xbfb8aa3b, v45
	v_exp_f32_e32 v48, v48
	v_exp_f32_e32 v49, v49
	s_nop 0
	v_pk_add_f32 v[48:49], v[48:49], 1.0 op_sel_hi:[1,0]
	v_rcp_f32_e32 v49, v49
; #define PG8_BAR __builtin_amdgcn_s_barrier()
; DI unsigned pk2(float lo, float hi) { const f32x2_t v = {lo, hi}; const bf16x2_t b = __builtin_convertvector(v, bf16x2_t); return __builtin_bit_cast(unsigned, b); }
; template <class Epi, class Sched, bool ALIGN_EPI = false, bool SP2 = false>
; __device__ __forceinline__ void gemm_phase(PG8_LAS unsigned char* lds, const Gemm g, const Sched& S, const Epi& E, const int tid) {
;     ...
;         if (!has_next) break;
; #pragma unroll
;         for (int a = 0; a < 2; ++a)
; #pragma unroll
;             for (int b = 0; b < 2; ++b)
; #pragma unroll
;                 for (int m = 0; m < 4; ++m)
; #pragma unroll
;                     for (int n = 0; n < 2; ++n) acc[a][b][m][n] = (f32x4){0.f, 0.f, 0.f, 0.f};
;         cur = nxt; cA = nA; cB = nB; ++ui;
;         if constexpr (ALIGN_EPI) { if (wr == 1) PG8_BAR; }
;     DI void operator()(const pg8::f32x4 (&acc)[2][2][4][2], const pg8::Unit& u, int wr, int wc, int fr, int fq) const {
;     ...
;             for (int m = 0; m < 4; ++m) {
;                 const int row = row0 + ai * 128 + m * 16; const float r = rs[ai][m];
;                 float hv[8];
; #pragma unroll
;                 for (int n = 0; n < 2; ++n) { const pg8::f32x4 g = acc[ai][0][m][n] * r, uu = acc[ai][1][m][n] * r;
; #pragma unroll
;                     for (int e = 0; e < 4; ++e) hv[4 * n + e] = g[e] * __frcp_rn(1.0f + __expf(-g[e])) * uu[e]; }
;                 u32x4 w; w.x = pk2(hv[0], hv[1]); w.y = pk2(hv[2], hv[3]); w.z = pk2(hv[4], hv[5]); w.w = pk2(hv[6], hv[7]);
;                 *(u32x4*)(H + (size_t)row * DFF + col0) = w;
	v_rcp_f32_e32 v48, v48
	s_nop 0
	v_pk_mul_f32 v[44:45], v[44:45], v[48:49]
	v_pk_mul_f32 v[40:41], v[40:41], v[44:45]
	v_pk_mul_f32 v[44:45], v[46:47], v[142:143] op_sel_hi:[1,0]
	v_mul_f32_e32 v46, 0xbfb8aa3b, v44
	v_mul_f32_e32 v47, 0xbfb8aa3b, v45
	v_exp_f32_e32 v46, v46
	v_exp_f32_e32 v47, v47
	s_nop 0
	v_pk_add_f32 v[46:47], v[46:47], 1.0 op_sel_hi:[1,0]
	v_rcp_f32_e32 v47, v47
	v_rcp_f32_e32 v46, v46
	s_nop 0
	v_pk_mul_f32 v[44:45], v[44:45], v[46:47]
	v_pk_mul_f32 v[42:43], v[42:43], v[44:45]
	v_mul_f32_e32 v44, 0xbfb8aa3b, v36
	v_mul_f32_e32 v45, 0xbfb8aa3b, v37
	v_exp_f32_e32 v44, v44
	v_exp_f32_e32 v45, v45
	s_nop 0
	v_pk_add_f32 v[44:45], v[44:45], 1.0 op_sel_hi:[1,0]
	v_rcp_f32_e32 v45, v45
	v_rcp_f32_e32 v44, v44
	s_nop 0
	v_pk_mul_f32 v[36:37], v[36:37], v[44:45]
	v_pk_mul_f32 v[36:37], v[32:33], v[36:37]
	v_pk_mul_f32 v[32:33], v[38:39], v[142:143] op_sel_hi:[1,0]
	v_mul_f32_e32 v38, 0xbfb8aa3b, v32
	v_mul_f32_e32 v39, 0xbfb8aa3b, v33
	v_exp_f32_e32 v38, v38
	v_exp_f32_e32 v39, v39
	s_nop 0
	v_pk_add_f32 v[38:39], v[38:39], 1.0 op_sel_hi:[1,0]
	v_rcp_f32_e32 v39, v39
	v_rcp_f32_e32 v38, v38
	s_nop 0
	v_pk_mul_f32 v[32:33], v[32:33], v[38:39]
	v_add_u32_e32 v44, 0x90, v151
	v_pk_mul_f32 v[38:39], v[34:35], v[32:33]
	v_cvt_pk_bf16_f32 v34, v36, v37
	v_mad_i64_i32 v[36:37], s[16:17], v44, s9, v[112:113]
	v_cvt_pk_bf16_f32 v32, v40, v41
	v_cvt_pk_bf16_f32 v33, v42, v43
	v_cvt_pk_bf16_f32 v35, v38, v39
	v_lshl_add_u64 v[36:37], v[36:37], 0, v[114:115]
	global_store_dwordx4 v[36:37], v[32:35], off
	s_nop 1
	v_mul_f32_e32 v32, 0xbfb8aa3b, v28
	v_mul_f32_e32 v33, 0xbfb8aa3b, v29
	v_exp_f32_e32 v32, v32
	v_exp_f32_e32 v33, v33
	s_nop 0
	v_pk_add_f32 v[32:33], v[32:33], 1.0 op_sel_hi:[1,0]
	v_rcp_f32_e32 v33, v33
	v_rcp_f32_e32 v32, v32
	s_nop 0
	v_pk_mul_f32 v[28:29], v[28:29], v[32:33]
	v_pk_mul_f32 v[24:25], v[24:25], v[28:29]
	v_pk_mul_f32 v[28:29], v[30:31], v[140:141] op_sel_hi:[1,0]
	v_mul_f32_e32 v30, 0xbfb8aa3b, v28
	v_mul_f32_e32 v31, 0xbfb8aa3b, v29
	v_exp_f32_e32 v30, v30
	v_exp_f32_e32 v31, v31
	s_nop 0
	v_pk_add_f32 v[30:31], v[30:31], 1.0 op_sel_hi:[1,0]
	v_rcp_f32_e32 v31, v31
	v_rcp_f32_e32 v30, v30
	s_nop 0
	v_pk_mul_f32 v[28:29], v[28:29], v[30:31]
	v_pk_mul_f32 v[26:27], v[26:27], v[28:29]
	v_mul_f32_e32 v28, 0xbfb8aa3b, v20
	v_mul_f32_e32 v29, 0xbfb8aa3b, v21
	v_exp_f32_e32 v28, v28
	v_exp_f32_e32 v29, v29
	s_nop 0
	v_pk_add_f32 v[28:29], v[28:29], 1.0 op_sel_hi:[1,0]
	v_rcp_f32_e32 v29, v29
	v_rcp_f32_e32 v28, v28
	s_nop 0
	v_pk_mul_f32 v[20:21], v[20:21], v[28:29]
	v_pk_mul_f32 v[20:21], v[16:17], v[20:21]
	v_pk_mul_f32 v[16:17], v[22:23], v[140:141] op_sel_hi:[1,0]
	v_mul_f32_e32 v22, 0xbfb8aa3b, v16
	v_mul_f32_e32 v23, 0xbfb8aa3b, v17
	v_exp_f32_e32 v22, v22
	v_exp_f32_e32 v23, v23
	s_nop 0
	v_pk_add_f32 v[22:23], v[22:23], 1.0 op_sel_hi:[1,0]
	v_rcp_f32_e32 v23, v23
	v_rcp_f32_e32 v22, v22
	s_nop 0
	v_pk_mul_f32 v[16:17], v[16:17], v[22:23]
	v_add_u32_e32 v28, 0xa0, v151
	v_pk_mul_f32 v[22:23], v[18:19], v[16:17]
	v_cvt_pk_bf16_f32 v18, v20, v21
	v_mad_i64_i32 v[20:21], s[16:17], v28, s9, v[112:113]
	v_cvt_pk_bf16_f32 v16, v24, v25
	v_cvt_pk_bf16_f32 v17, v26, v27
	v_cvt_pk_bf16_f32 v19, v22, v23
	v_lshl_add_u64 v[20:21], v[20:21], 0, v[114:115]
	global_store_dwordx4 v[20:21], v[16:19], off
	s_nop 1
	v_mul_f32_e32 v16, 0xbfb8aa3b, v12
	v_mul_f32_e32 v17, 0xbfb8aa3b, v13
	v_exp_f32_e32 v16, v16
	v_exp_f32_e32 v17, v17
	s_nop 0
	v_pk_add_f32 v[16:17], v[16:17], 1.0 op_sel_hi:[1,0]
	v_rcp_f32_e32 v17, v17
	v_rcp_f32_e32 v16, v16
	s_nop 0
	v_pk_mul_f32 v[12:13], v[12:13], v[16:17]
	v_pk_mul_f32 v[8:9], v[8:9], v[12:13]
	v_pk_mul_f32 v[12:13], v[14:15], v[138:139] op_sel_hi:[1,0]
	v_mul_f32_e32 v14, 0xbfb8aa3b, v12
	v_mul_f32_e32 v15, 0xbfb8aa3b, v13
	v_exp_f32_e32 v14, v14
	v_exp_f32_e32 v15, v15
	s_nop 0
	v_pk_add_f32 v[14:15], v[14:15], 1.0 op_sel_hi:[1,0]
	v_rcp_f32_e32 v15, v15
	v_rcp_f32_e32 v14, v14
	s_nop 0
	v_pk_mul_f32 v[12:13], v[12:13], v[14:15]
	v_pk_mul_f32 v[10:11], v[10:11], v[12:13]
	v_mul_f32_e32 v12, 0xbfb8aa3b, v4
	v_mul_f32_e32 v13, 0xbfb8aa3b, v5
	v_exp_f32_e32 v12, v12
	v_exp_f32_e32 v13, v13
	s_nop 0
	v_pk_add_f32 v[12:13], v[12:13], 1.0 op_sel_hi:[1,0]
	v_rcp_f32_e32 v13, v13
	v_rcp_f32_e32 v12, v12
	s_nop 0
	v_pk_mul_f32 v[4:5], v[4:5], v[12:13]
	v_pk_mul_f32 v[4:5], v[0:1], v[4:5]
	v_pk_mul_f32 v[0:1], v[6:7], v[138:139] op_sel_hi:[1,0]
	v_mul_f32_e32 v6, 0xbfb8aa3b, v0
	v_mul_f32_e32 v7, 0xbfb8aa3b, v1
	v_exp_f32_e32 v6, v6
	v_exp_f32_e32 v7, v7
	s_nop 0
	v_pk_add_f32 v[6:7], v[6:7], 1.0 op_sel_hi:[1,0]
	v_rcp_f32_e32 v7, v7
	v_rcp_f32_e32 v6, v6
	s_nop 0
	v_pk_mul_f32 v[0:1], v[0:1], v[6:7]
	v_add_u32_e32 v12, 0xb0, v151
	v_pk_mul_f32 v[6:7], v[2:3], v[0:1]
	v_cvt_pk_bf16_f32 v2, v4, v5
	v_mad_i64_i32 v[4:5], s[16:17], v12, s9, v[112:113]
	v_cvt_pk_bf16_f32 v0, v8, v9
	v_cvt_pk_bf16_f32 v1, v10, v11
	v_cvt_pk_bf16_f32 v3, v6, v7
	v_lshl_add_u64 v[4:5], v[4:5], 0, v[114:115]
	s_mov_b64 s[16:17], -1
	s_andn2_b64 vcc, exec, s[40:41]
	global_store_dwordx4 v[4:5], v[0:3], off
	s_cbranch_vccnz .LBB0_509
	s_andn2_b64 vcc, exec, s[2:3]
	s_cbranch_vccnz .LBB0_508
	s_barrier
	s_branch .LBB0_508

; DI float rowscale(const float* ss, int row) {
;     const f32x4* p = (const f32x4*)(ss + (size_t)row * 16);
;     const f32x4 a = p[0], b = p[1], c = p[2], d = p[3];
;     const float s = (((a.x + a.y) + (a.z + a.w)) + ((b.x + b.y) + (b.z + b.w))) + (((c.x + c.y) + (c.z + c.w)) + ((d.x + d.y) + (d.z + d.w)));
;     return rsqrtf(s * (1.0f / 1024.0f) + EPS);
; }
; DI void rowscales8(const float* ss, int rowbase, int fr, int fq, float (&r)[2][4]) {
;     const int lane = fq * 16 + fr;
;     const float rA = rowscale(ss, rowbase + lane), rB = rowscale(ss, rowbase + 128 + lane);
; #pragma unroll
;     for (int m = 0; m < 4; ++m) { r[0][m] = __shfl(rA, m * 16 + fr); r[1][m] = __shfl(rB, m * 16 + fr); }
; }
;     DI void operator()(const pg8::f32x4 (&acc)[2][2][4][2], const pg8::Unit& u, int wr, int wc, int fr, int fq) const {
;         const int row0 = u.pm * 256 + wr * 64 + fr, col0 = u.pn * 256 + wc * 32 + 8 * fq;
;         float rs[2][4];
;         if (ss) rowscales8(ss, u.pm * 256 + wr * 64, fr, fq, rs);
.Lmy_kdone_3:
.LBB0_624:
	s_lshl_b32 s37, s97, 8
	s_andn2_b64 vcc, exec, s[30:31]
	s_add_i32 s37, s37, s81
	s_cbranch_vccnz .LBB0_626
	v_or_b32_e32 v144, s37, v170
	v_ashrrev_i32_e32 v145, 31, v144
	v_lshlrev_b64 v[144:145], 6, v[144:145]
	v_lshl_add_u64 v[156:157], s[4:5], 0, v[144:145]
	global_load_dwordx4 v[144:147], v[156:157], off offset:16
	global_load_dwordx4 v[148:151], v[156:157], off offset:48
	global_load_dwordx4 v[152:155], v[156:157], off
	global_load_dwordx4 v[184:187], v[156:157], off offset:32
	v_or_b32_e32 v238, 0x80, v170
	v_add_u32_e32 v238, s37, v238
	v_ashrrev_i32_e32 v239, 31, v238
	v_lshlrev_b64 v[238:239], 6, v[238:239]
	v_lshl_add_u64 v[236:237], s[4:5], 0, v[238:239]
	global_load_dwordx4 v[220:223], v[236:237], off offset:16
	global_load_dwordx4 v[224:227], v[236:237], off offset:48
	global_load_dwordx4 v[228:231], v[236:237], off
	global_load_dwordx4 v[232:235], v[236:237], off offset:32
	s_mov_b32 s44, 0x3a800000
	s_waitcnt vmcnt(4)
	v_mov_b32_e32 v156, v152
	v_mov_b32_e32 v157, v184
	v_mov_b32_e32 v184, v153
	v_pk_add_f32 v[152:153], v[156:157], v[184:185]
	v_mov_b32_e32 v156, v154
	v_mov_b32_e32 v157, v186
	v_mov_b32_e32 v186, v155
	v_pk_add_f32 v[154:155], v[156:157], v[186:187]
	v_pk_add_f32 v[152:153], v[152:153], v[154:155]
	v_mov_b32_e32 v154, v144
	v_mov_b32_e32 v155, v148
	v_mov_b32_e32 v148, v145
	v_pk_add_f32 v[144:145], v[154:155], v[148:149]
	v_mov_b32_e32 v148, v146
	v_mov_b32_e32 v149, v150
	v_mov_b32_e32 v150, v147
	v_pk_add_f32 v[146:147], v[148:149], v[150:151]
	v_pk_add_f32 v[144:145], v[144:145], v[146:147]
	v_pk_add_f32 v[144:145], v[152:153], v[144:145]
	s_waitcnt vmcnt(0)
	v_mov_b64_e32 v[146:147], v[220:221]
	v_mov_b64_e32 v[148:149], v[222:223]
	v_mov_b64_e32 v[150:151], v[224:225]
	v_mov_b64_e32 v[152:153], v[226:227]
	v_mov_b64_e32 v[154:155], v[228:229]
	v_mov_b64_e32 v[156:157], v[230:231]
	v_mov_b64_e32 v[184:185], v[232:233]
	v_mov_b64_e32 v[186:187], v[234:235]
	v_mov_b32_e32 v178, v154
	v_mov_b32_e32 v179, v184
	v_mov_b32_e32 v184, v155
	v_pk_add_f32 v[154:155], v[178:179], v[184:185]
	v_mov_b32_e32 v178, v156
	v_mov_b32_e32 v179, v186
	v_mov_b32_e32 v186, v157
	v_pk_add_f32 v[156:157], v[178:179], v[186:187]
	v_pk_add_f32 v[154:155], v[154:155], v[156:157]
	v_mov_b32_e32 v156, v146
	v_mov_b32_e32 v157, v150
	v_mov_b32_e32 v150, v147
	v_pk_add_f32 v[146:147], v[156:157], v[150:151]
	v_mov_b32_e32 v150, v148
	v_mov_b32_e32 v151, v152
	v_mov_b32_e32 v152, v149
	v_pk_add_f32 v[148:149], v[150:151], v[152:153]
	v_pk_add_f32 v[146:147], v[146:147], v[148:149]
	v_mov_b32_e32 v149, v144
	v_pk_add_f32 v[146:147], v[154:155], v[146:147]
	v_mov_b32_e32 v148, v146
	v_mov_b32_e32 v144, v147
	v_pk_add_f32 v[144:145], v[148:149], v[144:145]
	v_pk_fma_f32 v[144:145], v[144:145], s[44:45], v[176:177] op_sel_hi:[1,0,0]
	v_mul_f32_e32 v146, 0x4b800000, v145
	v_cmp_gt_f32_e64 s[44:45], s39, v145
	v_cmp_gt_f32_e32 vcc, s39, v144
	s_nop 0
	v_cndmask_b32_e64 v145, v145, v146, s[44:45]
	v_rsq_f32_e32 v145, v145
	s_nop 0
	v_mul_f32_e32 v146, 0x45800000, v145
	v_cndmask_b32_e64 v145, v145, v146, s[44:45]
	v_mul_f32_e32 v146, 0x4b800000, v144
	v_cndmask_b32_e32 v144, v144, v146, vcc
	v_rsq_f32_e32 v144, v144
	s_nop 0
	v_mul_f32_e32 v146, 0x45800000, v144
	v_cndmask_b32_e32 v150, v144, v146, vcc
	v_and_or_b32 v144, v177, 64, v166
	v_lshlrev_b32_e32 v151, 2, v144
	ds_bpermute_b32 v152, v151, v145
	ds_bpermute_b32 v146, v151, v150
	ds_bpermute_b32 v153, v151, v145 offset:64
	ds_bpermute_b32 v147, v151, v150 offset:64
	ds_bpermute_b32 v148, v151, v145 offset:128
	ds_bpermute_b32 v144, v151, v150 offset:128
	ds_bpermute_b32 v149, v151, v145 offset:192
	ds_bpermute_b32 v145, v151, v150 offset:192
	s_branch .LBB0_627

; #define PG8_BAR __builtin_amdgcn_s_barrier()
; template <class Epi, class Sched, bool ALIGN_EPI = false, bool SP2 = false>
; __device__ __forceinline__ void gemm_phase(PG8_LAS unsigned char* lds, const Gemm g, const Sched& S, const Epi& E, const int tid) {
;     ...
;         if constexpr (ALIGN_EPI) { if (wr == 0) PG8_BAR; }
.LBB0_627:
	s_cmp_lg_u64 s[26:27], 0
	s_cbranch_scc0 .Lmy_ab3
	s_barrier
